# X51: X49 plus residual epilogues (down, w_out) requesting all 16 residual-tile pieces up front into borrowed registers (re-test of an earlier variant with the paired measurement)
# baseline (speedup 1.0000x reference)
;     __device__ __forceinline__ void operator()(const f32x4 (&acc)[2][2][4][2], const Unit& u, int wr, int wc, int fr, int fq, const Pre&) const {
;         const int row0 = u.pm * BM + wr * 64 + fr, col0 = u.pn * BM + wc * 32 + 8 * fq, wave = wr * 4 + wc, lane = fq * 16 + fr;
;         constexpr int NB = MK_LO ? 2 : 4;
; #pragma unroll
;         for (int ab = 0; ab < 8 / NB; ++ab) {
;             u32x4 hi[NB][2], lo[NB];
; #pragma unroll
;             for (int mm = 0; mm < NB; ++mm) { const int am = NB * ab + mm, ai = am >> 2, m = am & 3; if (MK_LO) lo[mm] = *(const u32x4*)(xl + lo_addr(u.pm, u.pn, am, wave, lane)); else lo[mm] = (u32x4){0x80808080u, 0x80808080u, 0x80808080u, 0x80808080u};
; #pragma unroll
;                 for (int bj = 0; bj < 2; ++bj) hi[mm][bj] = *(const u32x4*)(xh + (size_t)(row0 + ai * HALF + m * 16) * ldc + col0 + bj * HALF); }
; #pragma unroll
;             for (int mm = 0; mm < NB; ++mm) { const int am = NB * ab + mm, ai = am >> 2, m = am & 3; const int row = row0 + ai * HALF + m * 16; float ss = 0.f; u32x4 wl = {0u, 0u, 0u, 0u};
; #pragma unroll
;                 for (int bj = 0; bj < 2; ++bj) { const size_t o2 = (size_t)row * ldc + col0 + bj * HALF; u32x4 wh;
; #pragma unroll
;                     for (int q = 0; q < 4; ++q) { const unsigned h = hi[mm][bj][q], lw = lo[mm][2 * bj + (q >> 1)] >> (16 * (q & 1));
;                         float x0 = __builtin_bit_cast(float, h << 16), x1 = __builtin_bit_cast(float, h & 0xffff0000u); if (MK_LO) { x0 += lo_dec(h & 0xffffu, lw & 0xffu); x1 += lo_dec(h >> 16, (lw >> 8) & 0xffu); }
;                         x0 += acc[ai][bj][m][q >> 1][2 * (q & 1)] * scale; x1 += acc[ai][bj][m][q >> 1][2 * (q & 1) + 1] * scale;
;                         ss += x0 * x0 + x1 * x1;
;                         const unsigned nh = cvt_pk_bf16(x0, x1); wh[q] = nh;
;                         if (MK_LO) wl[2 * bj + (q >> 1)] |= (lo_enc(x0, nh & 0xffffu) | (lo_enc(x1, nh >> 16) << 8)) << (16 * (q & 1)); }
;                     *(u32x4*)(xh + o2) = wh; }
;                 if (MK_LO) *(u32x4*)(xl + lo_addr(u.pm, u.pn, am, wave, lane)) = wl;
;                 ss += __shfl_xor(ss, 16); ss += __shfl_xor(ss, 32);
;                 if (fq == 0) atomicAdd(rowss_out + row, (unsigned)(ss * 1024.0f + 0.5f)); } }
.LBB0_302:
	v_lshl_or_b32 v176, s75, 8, v163
	v_lshl_add_u32 v180, s72, 8, v1
	v_ashrrev_i32_e32 v177, 31, v176
	v_lshlrev_b64 v[216:217], 1, v[176:177]
	v_ashrrev_i32_e32 v181, 31, v180
	v_lshl_add_u64 v[178:179], s[96:97], 0, v[216:217]
	v_lshlrev_b64 v[218:219], 12, v[180:181]
	v_lshl_add_u64 v[134:135], v[178:179], 0, v[218:219]
	global_load_dwordx4 v[190:193], v[134:135], off
	global_load_dwordx4 v[212:215], v[134:135], off offset:256
	v_or_b32_e32 v186, 16, v180
	v_or_b32_e32 v184, 32, v180
	v_or_b32_e32 v182, 48, v180
	v_ashrrev_i32_e32 v187, 31, v186
	v_ashrrev_i32_e32 v185, 31, v184
	v_ashrrev_i32_e32 v183, 31, v182
	v_lshlrev_b64 v[134:135], 12, v[186:187]
	v_lshlrev_b64 v[136:137], 12, v[184:185]
	v_lshlrev_b64 v[138:139], 12, v[182:183]
	v_lshl_add_u64 v[134:135], v[178:179], 0, v[134:135]
	v_lshl_add_u64 v[136:137], v[178:179], 0, v[136:137]
	v_lshl_add_u64 v[220:221], v[178:179], 0, v[138:139]
	global_load_dwordx4 v[154:157], v[134:135], off
	global_load_dwordx4 v[150:153], v[134:135], off offset:256
	global_load_dwordx4 v[146:149], v[136:137], off
	global_load_dwordx4 v[142:145], v[136:137], off offset:256
	global_load_dwordx4 v[138:141], v[220:221], off
	s_nop 0
	global_load_dwordx4 v[134:137], v[220:221], off offset:256
	v_add_u32_e32 v226, 0x80, v180
	v_ashrrev_i32_e32 v227, 31, v226
	v_lshlrev_b64 v[226:227], 12, v[226:227]
	v_lshl_add_u64 v[226:227], v[178:179], 0, v[226:227]
	global_load_dwordx4 v[228:231], v[226:227], off
	global_load_dwordx4 v[232:235], v[226:227], off offset:256
	v_add_u32_e32 v226, 0x90, v180
	v_ashrrev_i32_e32 v227, 31, v226
	v_lshlrev_b64 v[226:227], 12, v[226:227]
	v_lshl_add_u64 v[226:227], v[178:179], 0, v[226:227]
	global_load_dwordx4 v[236:239], v[226:227], off
	global_load_dwordx4 v[240:243], v[226:227], off offset:256
	v_add_u32_e32 v226, 0xa0, v180
	v_ashrrev_i32_e32 v227, 31, v226
	v_lshlrev_b64 v[226:227], 12, v[226:227]
	v_lshl_add_u64 v[226:227], v[178:179], 0, v[226:227]
	global_load_dwordx4 v[244:247], v[226:227], off
	global_load_dwordx4 v[248:251], v[226:227], off offset:256
	v_add_u32_e32 v226, 0xb0, v180
	v_ashrrev_i32_e32 v227, 31, v226
	v_lshlrev_b64 v[226:227], 12, v[226:227]
	v_lshl_add_u64 v[226:227], v[178:179], 0, v[226:227]
	global_load_dwordx4 v[164:167], v[226:227], off
	global_load_dwordx4 v[200:203], v[226:227], off offset:256
	v_and_b32_e32 v211, 64, v199
	v_xor_b32_e32 v189, 16, v199
	v_add_u32_e32 v211, 64, v211
	v_xor_b32_e32 v220, 32, v199
	v_cmp_lt_i32_e32 vcc, v189, v211
	v_lshl_add_u64 v[218:219], s[96:97], 0, v[218:219]
	v_lshl_add_u64 v[216:217], v[218:219], 0, v[216:217]
	v_cndmask_b32_e32 v189, v199, v189, vcc
	v_cmp_lt_i32_e32 vcc, v220, v211
	v_lshlrev_b32_e32 v189, 2, v189
	s_waitcnt vmcnt(0)
	v_lshlrev_b32_e32 v218, 16, v190
	v_and_b32_e32 v190, 0xffff0000, v190
	v_lshlrev_b32_e32 v219, 16, v191
	v_and_b32_e32 v191, 0xffff0000, v191
	v_cndmask_b32_e32 v211, v199, v220, vcc
	v_lshlrev_b32_e32 v220, 16, v192
	v_and_b32_e32 v192, 0xffff0000, v192
	v_lshlrev_b32_e32 v221, 16, v193
	v_and_b32_e32 v193, 0xffff0000, v193
	v_fmac_f32_e32 v190, 0.5, v123
	v_fmac_f32_e32 v191, 0.5, v125
	v_fmac_f32_e32 v218, 0.5, v122
	v_fmac_f32_e32 v219, 0.5, v124
	v_fmac_f32_e32 v192, 0.5, v119
	v_fmac_f32_e32 v221, 0.5, v120
	v_fmac_f32_e32 v193, 0.5, v121
	v_mul_f32_e32 v120, v190, v190
	v_mul_f32_e32 v121, v191, v191
	v_lshlrev_b32_e32 v222, 16, v212
	v_and_b32_e32 v212, 0xffff0000, v212
	v_fmac_f32_e32 v220, 0.5, v118
	v_mul_f32_e32 v122, v192, v192
	v_fmac_f32_e32 v120, v218, v218
	v_fmac_f32_e32 v121, v219, v219
	v_lshlrev_b32_e32 v223, 16, v213
	v_and_b32_e32 v213, 0xffff0000, v213
	v_fmac_f32_e32 v212, 0.5, v131
	v_mul_f32_e32 v123, v193, v193
	v_fmac_f32_e32 v122, v220, v220
	v_add_f32_e32 v120, v120, v121
	v_lshlrev_b32_e32 v224, 16, v214
	v_and_b32_e32 v214, 0xffff0000, v214
	v_fmac_f32_e32 v222, 0.5, v130
	v_fmac_f32_e32 v213, 0.5, v133
	v_mul_f32_e32 v124, v212, v212
	v_fmac_f32_e32 v123, v221, v221
	v_add_f32_e32 v120, v122, v120
	v_lshlrev_b32_e32 v225, 16, v215
	v_and_b32_e32 v215, 0xffff0000, v215
	v_fmac_f32_e32 v223, 0.5, v132
	v_fmac_f32_e32 v214, 0.5, v127
	v_mul_f32_e32 v125, v213, v213
	v_fmac_f32_e32 v124, v222, v222
	v_add_f32_e32 v120, v123, v120
	v_fmac_f32_e32 v224, 0.5, v126
	v_fmac_f32_e32 v215, 0.5, v129
	v_mul_f32_e32 v126, v214, v214
	v_fmac_f32_e32 v125, v223, v223
	v_add_f32_e32 v120, v124, v120
	v_fmac_f32_e32 v225, 0.5, v128
	v_mul_f32_e32 v127, v215, v215
	v_fmac_f32_e32 v126, v224, v224
	v_add_f32_e32 v120, v125, v120
	v_fmac_f32_e32 v127, v225, v225
	v_add_f32_e32 v120, v126, v120
	v_add_f32_e32 v123, v127, v120
	ds_bpermute_b32 v124, v189, v123
	v_cvt_pk_bf16_f32 v118, v218, v190
	v_cvt_pk_bf16_f32 v119, v219, v191
	v_cvt_pk_bf16_f32 v120, v220, v192
	v_cvt_pk_bf16_f32 v121, v221, v193
	global_store_dwordx4 v[216:217], v[118:121], off
	v_cvt_pk_bf16_f32 v122, v222, v212
	s_waitcnt lgkmcnt(0)
	s_nop 0
	v_add_f32_e32 v119, v123, v124
	v_lshlrev_b32_e32 v118, 2, v211
	ds_bpermute_b32 v120, v118, v119
	v_cvt_pk_bf16_f32 v123, v223, v213
	v_cvt_pk_bf16_f32 v124, v224, v214
	v_cvt_pk_bf16_f32 v125, v225, v215
	global_store_dwordx4 v[216:217], v[122:125], off offset:256
	s_and_saveexec_b64 s[22:23], s[36:37]
	s_mov_b32 s69, 0x60000
	s_cbranch_execz .LBB0_304
	s_waitcnt lgkmcnt(0)
	v_add_f32_e32 v119, v119, v120
	v_fma_f32 v119, v119, s71, 0.5
	v_cvt_u32_f32_e32 v119, v119
	v_lshl_add_u64 v[120:121], v[180:181], 2, s[42:43]
	global_atomic_add v[120:121], v119, off

; __device__ __forceinline__ unsigned cvt_pk_bf16(float lo, float hi) { unsigned r; asm volatile("v_cvt_pk_bf16_f32 %0, %1, %2" : "=v"(r) : "v"(lo), "v"(hi)); return r; }
; __device__ __forceinline__ float lo_dec(unsigned hb, unsigned byte) { return ((float)byte - 128.0f) * lo_scale(hb); }
;     __device__ __forceinline__ void operator()(const f32x4 (&acc)[2][2][4][2], const Unit& u, int wr, int wc, int fr, int fq, const Pre&) const {
;     ...
;             for (int mm = 0; mm < NB; ++mm) { const int am = NB * ab + mm, ai = am >> 2, m = am & 3; if (MK_LO) lo[mm] = *(const u32x4*)(xl + lo_addr(u.pm, u.pn, am, wave, lane)); else lo[mm] = (u32x4){0x80808080u, 0x80808080u, 0x80808080u, 0x80808080u};
; #pragma unroll
;                 for (int bj = 0; bj < 2; ++bj) hi[mm][bj] = *(const u32x4*)(xh + (size_t)(row0 + ai * HALF + m * 16) * ldc + col0 + bj * HALF); }
; #pragma unroll
;             for (int mm = 0; mm < NB; ++mm) { const int am = NB * ab + mm, ai = am >> 2, m = am & 3; const int row = row0 + ai * HALF + m * 16; float ss = 0.f; u32x4 wl = {0u, 0u, 0u, 0u};
; #pragma unroll
;                 for (int bj = 0; bj < 2; ++bj) { const size_t o2 = (size_t)row * ldc + col0 + bj * HALF; u32x4 wh;
; #pragma unroll
;                     for (int q = 0; q < 4; ++q) { const unsigned h = hi[mm][bj][q], lw = lo[mm][2 * bj + (q >> 1)] >> (16 * (q & 1));
;                         float x0 = __builtin_bit_cast(float, h << 16), x1 = __builtin_bit_cast(float, h & 0xffff0000u); if (MK_LO) { x0 += lo_dec(h & 0xffffu, lw & 0xffu); x1 += lo_dec(h >> 16, (lw >> 8) & 0xffu); }
;                         x0 += acc[ai][bj][m][q >> 1][2 * (q & 1)] * scale; x1 += acc[ai][bj][m][q >> 1][2 * (q & 1) + 1] * scale;
;                         ss += x0 * x0 + x1 * x1;
;                         const unsigned nh = cvt_pk_bf16(x0, x1); wh[q] = nh;
;                         if (MK_LO) wl[2 * bj + (q >> 1)] |= (lo_enc(x0, nh & 0xffffu) | (lo_enc(x1, nh >> 16) << 8)) << (16 * (q & 1)); }
;                     *(u32x4*)(xh + o2) = wh; }
;                 if (MK_LO) *(u32x4*)(xl + lo_addr(u.pm, u.pn, am, wave, lane)) = wl;
;                 ss += __shfl_xor(ss, 16); ss += __shfl_xor(ss, 32);
;                 if (fq == 0) atomicAdd(rowss_out + row, (unsigned)(ss * 1024.0f + 0.5f)); } }
.LBB0_310:
	s_or_b64 exec, exec, s[22:23]
	v_add_u32_e32 v100, 0x80, v180
	v_ashrrev_i32_e32 v101, 31, v100
	v_lshlrev_b64 v[110:111], 12, v[100:101]
	s_waitcnt lgkmcnt(0)
	v_lshl_add_u64 v[70:71], v[178:179], 0, v[110:111]
	v_mov_b64_e32 v[102:103], v[228:229]
	v_mov_b64_e32 v[104:105], v[230:231]
	v_mov_b64_e32 v[106:107], v[232:233]
	v_mov_b64_e32 v[108:109], v[234:235]
	v_add_u32_e32 v98, 0x90, v180
	v_add_u32_e32 v96, 0xa0, v180
	v_add_u32_e32 v94, 0xb0, v180
	v_ashrrev_i32_e32 v99, 31, v98
	v_ashrrev_i32_e32 v97, 31, v96
	v_ashrrev_i32_e32 v95, 31, v94
	v_lshlrev_b64 v[70:71], 12, v[98:99]
	v_lshlrev_b64 v[72:73], 12, v[96:97]
	v_lshlrev_b64 v[74:75], 12, v[94:95]
	v_lshl_add_u64 v[70:71], v[178:179], 0, v[70:71]
	v_lshl_add_u64 v[72:73], v[178:179], 0, v[72:73]
	v_lshl_add_u64 v[112:113], v[178:179], 0, v[74:75]
	v_mov_b64_e32 v[90:91], v[236:237]
	v_mov_b64_e32 v[92:93], v[238:239]
	v_mov_b64_e32 v[86:87], v[240:241]
	v_mov_b64_e32 v[88:89], v[242:243]
	v_mov_b64_e32 v[82:83], v[244:245]
	v_mov_b64_e32 v[84:85], v[246:247]
	v_mov_b64_e32 v[78:79], v[248:249]
	v_mov_b64_e32 v[80:81], v[250:251]
	v_mov_b64_e32 v[74:75], v[164:165]
	v_mov_b64_e32 v[76:77], v[166:167]
	s_nop 0
	v_mov_b64_e32 v[70:71], v[200:201]
	v_mov_b64_e32 v[72:73], v[202:203]
	v_mov_b64_e32 v[164:165], 0x400
	v_mov_b64_e32 v[166:167], 0x3ff
	v_mov_b32_e32 v200, 0x7f800000
	v_mov_b32_e32 v201, 0x7fc00000
	v_mov_b32_e32 v202, 0xff800000
	v_mov_b32_e32 v203, 0x3000
	v_lshlrev_b32_e32 v112, 16, v102
	v_and_b32_e32 v102, 0xffff0000, v102
	v_lshlrev_b32_e32 v113, 16, v103
	v_and_b32_e32 v103, 0xffff0000, v103
	v_lshlrev_b32_e32 v114, 16, v104
	v_and_b32_e32 v104, 0xffff0000, v104
	v_fmac_f32_e32 v102, 0.5, v59
	v_fmac_f32_e32 v103, 0.5, v61
	v_lshlrev_b32_e32 v115, 16, v105
	v_and_b32_e32 v105, 0xffff0000, v105
	v_fmac_f32_e32 v112, 0.5, v58
	v_fmac_f32_e32 v113, 0.5, v60
	v_fmac_f32_e32 v104, 0.5, v55
	v_mul_f32_e32 v58, v102, v102
	v_mul_f32_e32 v59, v103, v103
	v_lshlrev_b32_e32 v116, 16, v106
	v_and_b32_e32 v106, 0xffff0000, v106
	v_fmac_f32_e32 v114, 0.5, v54
	v_fmac_f32_e32 v105, 0.5, v57
	v_mul_f32_e32 v60, v104, v104
	v_fmac_f32_e32 v58, v112, v112
	v_fmac_f32_e32 v59, v113, v113
	v_lshlrev_b32_e32 v117, 16, v107
	v_and_b32_e32 v107, 0xffff0000, v107
	v_lshlrev_b32_e32 v119, 16, v108
	v_fmac_f32_e32 v115, 0.5, v56
	v_fmac_f32_e32 v106, 0.5, v67
	v_mul_f32_e32 v61, v105, v105
	v_fmac_f32_e32 v60, v114, v114
	v_add_f32_e32 v58, v58, v59
	v_and_b32_e32 v108, 0xffff0000, v108
	v_fmac_f32_e32 v116, 0.5, v66
	v_fmac_f32_e32 v107, 0.5, v69
	v_fmac_f32_e32 v119, 0.5, v62
	v_mul_f32_e32 v62, v106, v106
	v_fmac_f32_e32 v61, v115, v115
	v_add_f32_e32 v58, v60, v58
	v_lshlrev_b32_e32 v120, 16, v109
	v_and_b32_e32 v109, 0xffff0000, v109
	v_fmac_f32_e32 v117, 0.5, v68
	v_fmac_f32_e32 v108, 0.5, v63
	v_mul_f32_e32 v63, v107, v107
	v_fmac_f32_e32 v62, v116, v116
	v_add_f32_e32 v58, v61, v58
	v_fmac_f32_e32 v120, 0.5, v64
	v_fmac_f32_e32 v109, 0.5, v65
	v_mul_f32_e32 v64, v108, v108
	v_fmac_f32_e32 v63, v117, v117
	v_add_f32_e32 v58, v62, v58
	v_mul_f32_e32 v65, v109, v109
	v_fmac_f32_e32 v64, v119, v119
	v_add_f32_e32 v58, v63, v58
	v_add_f32_e32 v58, v64, v58
	v_fmac_f32_e32 v65, v120, v120
	v_add_f32_e32 v62, v65, v58
	ds_bpermute_b32 v63, v189, v62
	v_lshl_add_u64 v[58:59], s[96:97], 0, v[110:111]
	v_cvt_pk_bf16_f32 v54, v112, v102
	v_lshl_add_u64 v[60:61], v[176:177], 1, v[58:59]
	v_cvt_pk_bf16_f32 v55, v113, v103
	v_cvt_pk_bf16_f32 v56, v114, v104
	v_cvt_pk_bf16_f32 v57, v115, v105
	global_store_dwordx4 v[60:61], v[54:57], off
	s_waitcnt lgkmcnt(0)
	s_nop 0
	v_add_f32_e32 v54, v62, v63
	ds_bpermute_b32 v55, v118, v54
	v_cvt_pk_bf16_f32 v56, v116, v106
	v_cvt_pk_bf16_f32 v57, v117, v107
	v_cvt_pk_bf16_f32 v58, v119, v108
	v_cvt_pk_bf16_f32 v59, v120, v109
	global_store_dwordx4 v[60:61], v[56:59], off offset:256
	s_and_saveexec_b64 s[22:23], s[36:37]
	s_cbranch_execz .LBB0_312
	s_waitcnt lgkmcnt(0)
	v_add_f32_e32 v54, v54, v55
	v_fma_f32 v54, v54, s71, 0.5
	v_cvt_u32_f32_e32 v56, v54
	v_lshl_add_u64 v[54:55], v[100:101], 2, s[42:43]
	global_atomic_add v[54:55], v56, off
.LBB0_312:
	s_or_b64 exec, exec, s[22:23]
	v_and_b32_e32 v57, 0xffff0000, v90
	v_lshlrev_b32_e32 v56, 16, v90
	v_fmac_f32_e32 v57, 0.5, v51
	v_fmac_f32_e32 v56, 0.5, v50
	v_mul_f32_e32 v51, v57, v57
	v_cvt_pk_bf16_f32 v50, v56, v57
	v_and_b32_e32 v57, 0xffff0000, v91
	v_fmac_f32_e32 v51, v56, v56
	v_lshlrev_b32_e32 v56, 16, v91
	v_fmac_f32_e32 v57, 0.5, v53
	v_fmac_f32_e32 v56, 0.5, v52
	v_mul_f32_e32 v52, v57, v57
	v_fmac_f32_e32 v52, v56, v56
	v_add_f32_e32 v52, v51, v52
	v_cvt_pk_bf16_f32 v51, v56, v57
	v_and_b32_e32 v56, 0xffff0000, v92
	v_lshlrev_b32_e32 v53, 16, v92
	v_fmac_f32_e32 v56, 0.5, v47
	v_fmac_f32_e32 v53, 0.5, v46
	v_mul_f32_e32 v46, v56, v56
	v_fmac_f32_e32 v46, v53, v53
	v_add_f32_e32 v46, v46, v52
	v_cvt_pk_bf16_f32 v52, v53, v56
	v_and_b32_e32 v53, 0xffff0000, v93
	v_lshlrev_b32_e32 v47, 16, v93
	v_fmac_f32_e32 v53, 0.5, v49
	v_fmac_f32_e32 v47, 0.5, v48
	v_mul_f32_e32 v48, v53, v53
	v_fmac_f32_e32 v48, v47, v47
	v_add_f32_e32 v46, v48, v46
	v_and_b32_e32 v48, 0xffff0000, v86
	v_cvt_pk_bf16_f32 v53, v47, v53
	v_lshlrev_b32_e32 v47, 16, v86
	v_fmac_f32_e32 v48, 0.5, v43
	v_fmac_f32_e32 v47, 0.5, v42
	v_mul_f32_e32 v42, v48, v48
	v_fmac_f32_e32 v42, v47, v47
	v_add_f32_e32 v42, v42, v46
	v_and_b32_e32 v46, 0xffff0000, v87
	v_lshlrev_b32_e32 v43, 16, v87
	v_fmac_f32_e32 v46, 0.5, v45
	v_and_b32_e32 v56, 0xffff0000, v88
	v_fmac_f32_e32 v43, 0.5, v44
	v_mul_f32_e32 v44, v46, v46
	v_lshlrev_b32_e32 v49, 16, v88
	v_fmac_f32_e32 v56, 0.5, v39
	v_and_b32_e32 v58, 0xffff0000, v89
	v_fmac_f32_e32 v44, v43, v43
	v_fmac_f32_e32 v49, 0.5, v38
	v_mul_f32_e32 v38, v56, v56
	v_lshlrev_b32_e32 v57, 16, v89
	v_fmac_f32_e32 v58, 0.5, v41
	v_add_f32_e32 v42, v44, v42
	v_fmac_f32_e32 v38, v49, v49
	v_fmac_f32_e32 v57, 0.5, v40
	v_mul_f32_e32 v39, v58, v58
	v_add_f32_e32 v38, v38, v42
	v_fmac_f32_e32 v39, v57, v57
	v_add_f32_e32 v41, v39, v38
	ds_bpermute_b32 v42, v189, v41
	s_waitcnt lgkmcnt(1)
	v_lshlrev_b64 v[54:55], 11, v[98:99]
	v_lshl_add_u64 v[38:39], v[54:55], 1, s[96:97]
	v_lshl_add_u64 v[44:45], v[176:177], 1, v[38:39]
	global_store_dwordx4 v[44:45], v[50:53], off
	s_waitcnt lgkmcnt(0)
	v_add_f32_e32 v38, v41, v42
	ds_bpermute_b32 v39, v118, v38
	v_cvt_pk_bf16_f32 v40, v47, v48
	v_cvt_pk_bf16_f32 v41, v43, v46
	v_cvt_pk_bf16_f32 v42, v49, v56
	v_cvt_pk_bf16_f32 v43, v57, v58
	global_store_dwordx4 v[44:45], v[40:43], off offset:256
	s_and_saveexec_b64 s[22:23], s[36:37]
	s_cbranch_execz .LBB0_314
	s_waitcnt lgkmcnt(0)
	v_add_f32_e32 v38, v38, v39
	v_fma_f32 v38, v38, s71, 0.5
	v_cvt_u32_f32_e32 v40, v38
	v_lshl_add_u64 v[38:39], v[98:99], 2, s[42:43]
	global_atomic_add v[38:39], v40, off
; __device__ __forceinline__ unsigned cvt_pk_bf16(float lo, float hi) { unsigned r; asm volatile("v_cvt_pk_bf16_f32 %0, %1, %2" : "=v"(r) : "v"(lo), "v"(hi)); return r; }
; __device__ __forceinline__ float lo_dec(unsigned hb, unsigned byte) { return ((float)byte - 128.0f) * lo_scale(hb); }
; __device__ __forceinline__ unsigned lo_enc(float x, unsigned hb) { const float hf = __builtin_bit_cast(float, hb << 16); float t = (x - hf) * lo_inv(hb) + 128.0f; t = fminf(fmaxf(t, 1.0f), 255.0f); return (unsigned)__builtin_rintf(t); }
; __device__ __forceinline__ size_t lo_addr(int pm, int pn, int am, int wave, int lane) { return ((((size_t)(pm * 8 + pn) * 8 + am) * 8 + wave) * 64 + lane) * 16; }
;     __device__ __forceinline__ void operator()(const f32x4 (&acc)[2][2][4][2], const Unit& u, int wr, int wc, int fr, int fq, const Pre&) const {
;     ...
;             for (int mm = 0; mm < NB; ++mm) { const int am = NB * ab + mm, ai = am >> 2, m = am & 3; const int row = row0 + ai * HALF + m * 16; float ss = 0.f; u32x4 wl = {0u, 0u, 0u, 0u};
; #pragma unroll
;                 for (int bj = 0; bj < 2; ++bj) { const size_t o2 = (size_t)row * ldc + col0 + bj * HALF; u32x4 wh;
; #pragma unroll
;                     for (int q = 0; q < 4; ++q) { const unsigned h = hi[mm][bj][q], lw = lo[mm][2 * bj + (q >> 1)] >> (16 * (q & 1));
;                         float x0 = __builtin_bit_cast(float, h << 16), x1 = __builtin_bit_cast(float, h & 0xffff0000u); if (MK_LO) { x0 += lo_dec(h & 0xffffu, lw & 0xffu); x1 += lo_dec(h >> 16, (lw >> 8) & 0xffu); }
;                         x0 += acc[ai][bj][m][q >> 1][2 * (q & 1)] * scale; x1 += acc[ai][bj][m][q >> 1][2 * (q & 1) + 1] * scale;
;                         ss += x0 * x0 + x1 * x1;
;                         const unsigned nh = cvt_pk_bf16(x0, x1); wh[q] = nh;
;                         if (MK_LO) wl[2 * bj + (q >> 1)] |= (lo_enc(x0, nh & 0xffffu) | (lo_enc(x1, nh >> 16) << 8)) << (16 * (q & 1)); }
;                     *(u32x4*)(xh + o2) = wh; }
;                 if (MK_LO) *(u32x4*)(xl + lo_addr(u.pm, u.pn, am, wave, lane)) = wl;
;                 ss += __shfl_xor(ss, 16); ss += __shfl_xor(ss, 32);
;                 if (fq == 0) atomicAdd(rowss_out + row, (unsigned)(ss * 1024.0f + 0.5f)); } }
.LBB0_314:
	s_or_b64 exec, exec, s[22:23]
	v_and_b32_e32 v41, 0xffff0000, v82
	v_lshlrev_b32_e32 v40, 16, v82
	v_fmac_f32_e32 v41, 0.5, v35
	v_fmac_f32_e32 v40, 0.5, v34
	v_mul_f32_e32 v35, v41, v41
	v_cvt_pk_bf16_f32 v34, v40, v41
	v_and_b32_e32 v41, 0xffff0000, v83
	v_fmac_f32_e32 v35, v40, v40
	v_lshlrev_b32_e32 v40, 16, v83
	v_fmac_f32_e32 v41, 0.5, v37
	v_fmac_f32_e32 v40, 0.5, v36
	v_mul_f32_e32 v36, v41, v41
	v_fmac_f32_e32 v36, v40, v40
	v_add_f32_e32 v36, v35, v36
	v_cvt_pk_bf16_f32 v35, v40, v41
	v_and_b32_e32 v40, 0xffff0000, v84
	v_lshlrev_b32_e32 v37, 16, v84
	v_fmac_f32_e32 v40, 0.5, v31
	v_fmac_f32_e32 v37, 0.5, v30
	v_mul_f32_e32 v30, v40, v40
	v_fmac_f32_e32 v30, v37, v37
	v_add_f32_e32 v30, v30, v36
	v_cvt_pk_bf16_f32 v36, v37, v40
	v_and_b32_e32 v37, 0xffff0000, v85
	v_lshlrev_b32_e32 v31, 16, v85
	v_fmac_f32_e32 v37, 0.5, v33
	v_fmac_f32_e32 v31, 0.5, v32
	v_mul_f32_e32 v32, v37, v37
	v_fmac_f32_e32 v32, v31, v31
	v_add_f32_e32 v30, v32, v30
	v_and_b32_e32 v32, 0xffff0000, v78
	v_cvt_pk_bf16_f32 v37, v31, v37
	v_lshlrev_b32_e32 v31, 16, v78
	v_fmac_f32_e32 v32, 0.5, v27
	v_fmac_f32_e32 v31, 0.5, v26
	v_mul_f32_e32 v26, v32, v32
	v_fmac_f32_e32 v26, v31, v31
	v_add_f32_e32 v26, v26, v30
	v_and_b32_e32 v30, 0xffff0000, v79
	v_lshlrev_b32_e32 v27, 16, v79
	v_fmac_f32_e32 v30, 0.5, v29
	v_and_b32_e32 v40, 0xffff0000, v80
	v_fmac_f32_e32 v27, 0.5, v28
	v_mul_f32_e32 v28, v30, v30
	v_lshlrev_b32_e32 v33, 16, v80
	v_fmac_f32_e32 v40, 0.5, v23
	v_and_b32_e32 v42, 0xffff0000, v81
	v_fmac_f32_e32 v28, v27, v27
	v_fmac_f32_e32 v33, 0.5, v22
	v_mul_f32_e32 v22, v40, v40
	v_lshlrev_b32_e32 v41, 16, v81
	v_fmac_f32_e32 v42, 0.5, v25
	v_add_f32_e32 v26, v28, v26
	v_fmac_f32_e32 v22, v33, v33
	v_fmac_f32_e32 v41, 0.5, v24
	v_mul_f32_e32 v23, v42, v42
	v_add_f32_e32 v22, v22, v26
	v_fmac_f32_e32 v23, v41, v41
	v_add_f32_e32 v25, v23, v22
	ds_bpermute_b32 v26, v189, v25
	s_waitcnt lgkmcnt(1)
	v_lshlrev_b64 v[38:39], 11, v[96:97]
	v_lshl_add_u64 v[22:23], v[38:39], 1, s[96:97]
	v_lshl_add_u64 v[28:29], v[176:177], 1, v[22:23]
	global_store_dwordx4 v[28:29], v[34:37], off
	s_waitcnt lgkmcnt(0)
	v_add_f32_e32 v22, v25, v26
	ds_bpermute_b32 v23, v118, v22
	v_cvt_pk_bf16_f32 v24, v31, v32
	v_cvt_pk_bf16_f32 v25, v27, v30
	v_cvt_pk_bf16_f32 v26, v33, v40
	v_cvt_pk_bf16_f32 v27, v41, v42
	global_store_dwordx4 v[28:29], v[24:27], off offset:256
	s_and_saveexec_b64 s[22:23], s[36:37]
	s_cbranch_execz .LBB0_316
	s_waitcnt lgkmcnt(0)
	v_add_f32_e32 v22, v22, v23
	v_fma_f32 v22, v22, s71, 0.5
	v_cvt_u32_f32_e32 v24, v22
	v_lshl_add_u64 v[22:23], v[96:97], 2, s[42:43]
	global_atomic_add v[22:23], v24, off
.LBB0_316:
	s_or_b64 exec, exec, s[22:23]
	v_and_b32_e32 v25, 0xffff0000, v74
	v_lshlrev_b32_e32 v24, 16, v74
	v_fmac_f32_e32 v25, 0.5, v19
	v_fmac_f32_e32 v24, 0.5, v18
	v_mul_f32_e32 v19, v25, v25
	v_cvt_pk_bf16_f32 v18, v24, v25
	v_and_b32_e32 v25, 0xffff0000, v75
	v_fmac_f32_e32 v19, v24, v24
	v_lshlrev_b32_e32 v24, 16, v75
	v_fmac_f32_e32 v25, 0.5, v21
	v_fmac_f32_e32 v24, 0.5, v20
	v_mul_f32_e32 v20, v25, v25
	v_fmac_f32_e32 v20, v24, v24
	v_add_f32_e32 v20, v19, v20
	v_cvt_pk_bf16_f32 v19, v24, v25
	v_and_b32_e32 v24, 0xffff0000, v76
	v_lshlrev_b32_e32 v21, 16, v76
	v_fmac_f32_e32 v24, 0.5, v15
	v_fmac_f32_e32 v21, 0.5, v14
	v_mul_f32_e32 v14, v24, v24
	v_fmac_f32_e32 v14, v21, v21
	v_add_f32_e32 v14, v14, v20
	v_cvt_pk_bf16_f32 v20, v21, v24
	v_and_b32_e32 v21, 0xffff0000, v77
	v_lshlrev_b32_e32 v15, 16, v77
	v_fmac_f32_e32 v21, 0.5, v17
	v_fmac_f32_e32 v15, 0.5, v16
	v_mul_f32_e32 v16, v21, v21
	v_fmac_f32_e32 v16, v15, v15
	v_add_f32_e32 v14, v16, v14
	v_and_b32_e32 v16, 0xffff0000, v70
	v_cvt_pk_bf16_f32 v21, v15, v21
	v_lshlrev_b32_e32 v15, 16, v70
	v_fmac_f32_e32 v16, 0.5, v11
	v_fmac_f32_e32 v15, 0.5, v10
	v_mul_f32_e32 v10, v16, v16
	v_fmac_f32_e32 v10, v15, v15
	v_add_f32_e32 v10, v10, v14
	v_and_b32_e32 v14, 0xffff0000, v71
	v_lshlrev_b32_e32 v11, 16, v71
	v_fmac_f32_e32 v14, 0.5, v13
	v_and_b32_e32 v24, 0xffff0000, v72
	v_fmac_f32_e32 v11, 0.5, v12
	v_mul_f32_e32 v12, v14, v14
	v_lshlrev_b32_e32 v17, 16, v72
	v_fmac_f32_e32 v24, 0.5, v7
	v_and_b32_e32 v26, 0xffff0000, v73
	v_fmac_f32_e32 v12, v11, v11
	v_fmac_f32_e32 v17, 0.5, v6
	v_mul_f32_e32 v6, v24, v24
	v_lshlrev_b32_e32 v25, 16, v73
	v_fmac_f32_e32 v26, 0.5, v9
	v_add_f32_e32 v10, v12, v10
	v_fmac_f32_e32 v6, v17, v17
	v_fmac_f32_e32 v25, 0.5, v8
	v_mul_f32_e32 v7, v26, v26
	v_add_f32_e32 v6, v6, v10
	v_fmac_f32_e32 v7, v25, v25
	v_add_f32_e32 v9, v7, v6
	ds_bpermute_b32 v10, v189, v9
	s_waitcnt lgkmcnt(1)
	v_lshlrev_b64 v[22:23], 11, v[94:95]
	v_lshl_add_u64 v[6:7], v[22:23], 1, s[96:97]
	v_lshl_add_u64 v[12:13], v[176:177], 1, v[6:7]
	global_store_dwordx4 v[12:13], v[18:21], off
	s_waitcnt lgkmcnt(0)
	v_add_f32_e32 v6, v9, v10
	ds_bpermute_b32 v7, v118, v6
	v_cvt_pk_bf16_f32 v8, v15, v16
	v_cvt_pk_bf16_f32 v9, v11, v14
	v_cvt_pk_bf16_f32 v10, v17, v24
	v_cvt_pk_bf16_f32 v11, v25, v26
	global_store_dwordx4 v[12:13], v[8:11], off offset:256
	s_and_saveexec_b64 s[22:23], s[36:37]
	s_cbranch_execz .LBB0_318
	s_waitcnt lgkmcnt(0)
	v_add_f32_e32 v6, v6, v7
	v_fma_f32 v6, v6, s71, 0.5
	v_cvt_u32_f32_e32 v6, v6
	v_lshl_add_u64 v[8:9], v[94:95], 2, s[42:43]
	global_atomic_add v[8:9], v6, off

;     __device__ __forceinline__ void operator()(const f32x4 (&acc)[2][2][4][2], const Unit& u, int wr, int wc, int fr, int fq, const Pre&) const {
;         const int row0 = u.pm * BM + wr * 64 + fr, col0 = u.pn * BM + wc * 32 + 8 * fq, wave = wr * 4 + wc, lane = fq * 16 + fr;
;         constexpr int NB = MK_LO ? 2 : 4;
; #pragma unroll
;         for (int ab = 0; ab < 8 / NB; ++ab) {
;             u32x4 hi[NB][2], lo[NB];
; #pragma unroll
;             for (int mm = 0; mm < NB; ++mm) { const int am = NB * ab + mm, ai = am >> 2, m = am & 3; if (MK_LO) lo[mm] = *(const u32x4*)(xl + lo_addr(u.pm, u.pn, am, wave, lane)); else lo[mm] = (u32x4){0x80808080u, 0x80808080u, 0x80808080u, 0x80808080u};
; #pragma unroll
;                 for (int bj = 0; bj < 2; ++bj) hi[mm][bj] = *(const u32x4*)(xh + (size_t)(row0 + ai * HALF + m * 16) * ldc + col0 + bj * HALF); }
; #pragma unroll
;             for (int mm = 0; mm < NB; ++mm) { const int am = NB * ab + mm, ai = am >> 2, m = am & 3; const int row = row0 + ai * HALF + m * 16; float ss = 0.f; u32x4 wl = {0u, 0u, 0u, 0u};
; #pragma unroll
;                 for (int bj = 0; bj < 2; ++bj) { const size_t o2 = (size_t)row * ldc + col0 + bj * HALF; u32x4 wh;
; #pragma unroll
;                     for (int q = 0; q < 4; ++q) { const unsigned h = hi[mm][bj][q], lw = lo[mm][2 * bj + (q >> 1)] >> (16 * (q & 1));
;                         float x0 = __builtin_bit_cast(float, h << 16), x1 = __builtin_bit_cast(float, h & 0xffff0000u); if (MK_LO) { x0 += lo_dec(h & 0xffffu, lw & 0xffu); x1 += lo_dec(h >> 16, (lw >> 8) & 0xffu); }
;                         x0 += acc[ai][bj][m][q >> 1][2 * (q & 1)] * scale; x1 += acc[ai][bj][m][q >> 1][2 * (q & 1) + 1] * scale;
;                         ss += x0 * x0 + x1 * x1;
;                         const unsigned nh = cvt_pk_bf16(x0, x1); wh[q] = nh;
;                         if (MK_LO) wl[2 * bj + (q >> 1)] |= (lo_enc(x0, nh & 0xffffu) | (lo_enc(x1, nh >> 16) << 8)) << (16 * (q & 1)); }
;                     *(u32x4*)(xh + o2) = wh; }
;                 if (MK_LO) *(u32x4*)(xl + lo_addr(u.pm, u.pn, am, wave, lane)) = wl;
;                 ss += __shfl_xor(ss, 16); ss += __shfl_xor(ss, 32);
;                 if (fq == 0) atomicAdd(rowss_out + row, (unsigned)(ss * 1024.0f + 0.5f)); } }
.LBB0_1741:
	v_lshl_or_b32 v176, s65, 8, v163
	v_lshl_add_u32 v180, s33, 8, v1
	v_ashrrev_i32_e32 v177, 31, v176
	v_lshlrev_b64 v[214:215], 1, v[176:177]
	v_ashrrev_i32_e32 v181, 31, v180
	v_lshl_add_u64 v[178:179], s[96:97], 0, v[214:215]
	v_lshlrev_b64 v[216:217], 12, v[180:181]
	v_lshl_add_u64 v[134:135], v[178:179], 0, v[216:217]
	global_load_dwordx4 v[190:193], v[134:135], off
	global_load_dwordx4 v[210:213], v[134:135], off offset:256
	v_or_b32_e32 v186, 16, v180
	v_or_b32_e32 v184, 32, v180
	v_or_b32_e32 v182, 48, v180
	v_ashrrev_i32_e32 v187, 31, v186
	v_ashrrev_i32_e32 v185, 31, v184
	v_ashrrev_i32_e32 v183, 31, v182
	v_lshlrev_b64 v[134:135], 12, v[186:187]
	v_lshlrev_b64 v[136:137], 12, v[184:185]
	v_lshlrev_b64 v[138:139], 12, v[182:183]
	v_lshl_add_u64 v[134:135], v[178:179], 0, v[134:135]
	v_lshl_add_u64 v[136:137], v[178:179], 0, v[136:137]
	v_lshl_add_u64 v[218:219], v[178:179], 0, v[138:139]
	global_load_dwordx4 v[154:157], v[134:135], off
	global_load_dwordx4 v[150:153], v[134:135], off offset:256
	global_load_dwordx4 v[146:149], v[136:137], off
	global_load_dwordx4 v[142:145], v[136:137], off offset:256
	global_load_dwordx4 v[138:141], v[218:219], off
	s_nop 0
	global_load_dwordx4 v[134:137], v[218:219], off offset:256
	v_add_u32_e32 v226, 0x80, v180
	v_ashrrev_i32_e32 v227, 31, v226
	v_lshlrev_b64 v[226:227], 12, v[226:227]
	v_lshl_add_u64 v[226:227], v[178:179], 0, v[226:227]
	global_load_dwordx4 v[228:231], v[226:227], off
	global_load_dwordx4 v[232:235], v[226:227], off offset:256
	v_add_u32_e32 v226, 0x90, v180
	v_ashrrev_i32_e32 v227, 31, v226
	v_lshlrev_b64 v[226:227], 12, v[226:227]
	v_lshl_add_u64 v[226:227], v[178:179], 0, v[226:227]
	global_load_dwordx4 v[236:239], v[226:227], off
	global_load_dwordx4 v[240:243], v[226:227], off offset:256
	v_add_u32_e32 v226, 0xa0, v180
	v_ashrrev_i32_e32 v227, 31, v226
	v_lshlrev_b64 v[226:227], 12, v[226:227]
	v_lshl_add_u64 v[226:227], v[178:179], 0, v[226:227]
	global_load_dwordx4 v[244:247], v[226:227], off
	global_load_dwordx4 v[248:251], v[226:227], off offset:256
	v_add_u32_e32 v226, 0xb0, v180
	v_ashrrev_i32_e32 v227, 31, v226
	v_lshlrev_b64 v[226:227], 12, v[226:227]
	v_lshl_add_u64 v[226:227], v[178:179], 0, v[226:227]
	global_load_dwordx4 v[164:167], v[226:227], off
	global_load_dwordx4 v[200:203], v[226:227], off offset:256
	v_and_b32_e32 v218, 64, v199
	v_xor_b32_e32 v189, 16, v199
	v_add_u32_e32 v218, 64, v218
	v_xor_b32_e32 v219, 32, v199
	v_cmp_lt_i32_e32 vcc, v189, v218
	v_lshl_add_u64 v[216:217], s[96:97], 0, v[216:217]
	v_lshl_add_u64 v[214:215], v[216:217], 0, v[214:215]
	v_cndmask_b32_e32 v189, v199, v189, vcc
	v_cmp_lt_i32_e32 vcc, v219, v218
	v_lshlrev_b32_e32 v189, 2, v189
	s_waitcnt vmcnt(0)
	v_lshlrev_b32_e32 v216, 16, v190
	v_and_b32_e32 v190, 0xffff0000, v190
	v_lshlrev_b32_e32 v217, 16, v191
	v_and_b32_e32 v191, 0xffff0000, v191
	v_cndmask_b32_e32 v218, v199, v219, vcc
	v_lshlrev_b32_e32 v219, 16, v192
	v_and_b32_e32 v192, 0xffff0000, v192
	v_lshlrev_b32_e32 v220, 16, v193
	v_add_f32_e32 v123, v123, v190
	v_add_f32_e32 v125, v125, v191
	v_and_b32_e32 v193, 0xffff0000, v193
	v_add_f32_e32 v122, v122, v216
	v_add_f32_e32 v124, v124, v217
	v_add_f32_e32 v190, v118, v219
	v_add_f32_e32 v191, v119, v192
	v_add_f32_e32 v192, v120, v220
	v_mul_f32_e32 v120, v123, v123
	v_cvt_pk_bf16_f32 v118, v122, v123
	v_mul_f32_e32 v123, v125, v125
	v_lshlrev_b32_e32 v221, 16, v210
	v_and_b32_e32 v210, 0xffff0000, v210
	v_add_f32_e32 v121, v121, v193
	v_cvt_pk_bf16_f32 v119, v124, v125
	v_mul_f32_e32 v125, v191, v191
	v_fmac_f32_e32 v120, v122, v122
	v_fmac_f32_e32 v123, v124, v124
	v_lshlrev_b32_e32 v222, 16, v211
	v_and_b32_e32 v211, 0xffff0000, v211
	v_add_f32_e32 v131, v131, v210
	v_mul_f32_e32 v193, v121, v121
	v_fmac_f32_e32 v125, v190, v190
	v_add_f32_e32 v120, v120, v123
	v_lshlrev_b32_e32 v223, 16, v212
	v_and_b32_e32 v212, 0xffff0000, v212
	v_add_f32_e32 v130, v130, v221
	v_add_f32_e32 v133, v133, v211
	v_mul_f32_e32 v210, v131, v131
	v_fmac_f32_e32 v193, v192, v192
	v_add_f32_e32 v120, v125, v120
	v_lshlrev_b32_e32 v224, 16, v213
	v_and_b32_e32 v213, 0xffff0000, v213
	v_add_f32_e32 v132, v132, v222
	v_add_f32_e32 v127, v127, v212
	v_mul_f32_e32 v211, v133, v133
	v_fmac_f32_e32 v210, v130, v130
	v_add_f32_e32 v120, v193, v120
	v_add_f32_e32 v126, v126, v223
	v_add_f32_e32 v129, v129, v213
	v_mul_f32_e32 v212, v127, v127
	v_fmac_f32_e32 v211, v132, v132
	v_add_f32_e32 v120, v210, v120
	v_add_f32_e32 v128, v128, v224
	v_mul_f32_e32 v213, v129, v129
	v_fmac_f32_e32 v212, v126, v126
	v_add_f32_e32 v120, v211, v120
	v_fmac_f32_e32 v213, v128, v128
	v_add_f32_e32 v120, v212, v120
	v_add_f32_e32 v123, v213, v120
	ds_bpermute_b32 v124, v189, v123
	v_cvt_pk_bf16_f32 v120, v190, v191
	v_cvt_pk_bf16_f32 v121, v192, v121
	global_store_dwordx4 v[214:215], v[118:121], off
	v_cvt_pk_bf16_f32 v122, v130, v131
	s_waitcnt lgkmcnt(0)
	s_nop 0
	v_add_f32_e32 v119, v123, v124
	v_lshlrev_b32_e32 v118, 2, v218
	ds_bpermute_b32 v120, v118, v119
	v_cvt_pk_bf16_f32 v123, v132, v133
	v_cvt_pk_bf16_f32 v124, v126, v127
	v_cvt_pk_bf16_f32 v125, v128, v129
	global_store_dwordx4 v[214:215], v[122:125], off offset:256
	s_and_saveexec_b64 s[48:49], s[36:37]
	s_mov_b32 s71, 0x44800000
	s_mov_b32 s69, 0x60000
	s_cbranch_execz .LBB0_1743
	s_waitcnt lgkmcnt(0)
	v_add_f32_e32 v119, v119, v120
	v_fma_f32 v119, v119, s71, 0.5
	v_cvt_u32_f32_e32 v119, v119
	v_lshl_add_u64 v[120:121], v[180:181], 2, s[26:27]
	global_atomic_add v[120:121], v119, off

; __device__ __forceinline__ unsigned cvt_pk_bf16(float lo, float hi) { unsigned r; asm volatile("v_cvt_pk_bf16_f32 %0, %1, %2" : "=v"(r) : "v"(lo), "v"(hi)); return r; }
; __device__ __forceinline__ float lo_dec(unsigned hb, unsigned byte) { return ((float)byte - 128.0f) * lo_scale(hb); }
;     __device__ __forceinline__ void operator()(const f32x4 (&acc)[2][2][4][2], const Unit& u, int wr, int wc, int fr, int fq, const Pre&) const {
;     ...
;             for (int mm = 0; mm < NB; ++mm) { const int am = NB * ab + mm, ai = am >> 2, m = am & 3; if (MK_LO) lo[mm] = *(const u32x4*)(xl + lo_addr(u.pm, u.pn, am, wave, lane)); else lo[mm] = (u32x4){0x80808080u, 0x80808080u, 0x80808080u, 0x80808080u};
; #pragma unroll
;                 for (int bj = 0; bj < 2; ++bj) hi[mm][bj] = *(const u32x4*)(xh + (size_t)(row0 + ai * HALF + m * 16) * ldc + col0 + bj * HALF); }
; #pragma unroll
;             for (int mm = 0; mm < NB; ++mm) { const int am = NB * ab + mm, ai = am >> 2, m = am & 3; const int row = row0 + ai * HALF + m * 16; float ss = 0.f; u32x4 wl = {0u, 0u, 0u, 0u};
; #pragma unroll
;                 for (int bj = 0; bj < 2; ++bj) { const size_t o2 = (size_t)row * ldc + col0 + bj * HALF; u32x4 wh;
; #pragma unroll
;                     for (int q = 0; q < 4; ++q) { const unsigned h = hi[mm][bj][q], lw = lo[mm][2 * bj + (q >> 1)] >> (16 * (q & 1));
;                         float x0 = __builtin_bit_cast(float, h << 16), x1 = __builtin_bit_cast(float, h & 0xffff0000u); if (MK_LO) { x0 += lo_dec(h & 0xffffu, lw & 0xffu); x1 += lo_dec(h >> 16, (lw >> 8) & 0xffu); }
;                         x0 += acc[ai][bj][m][q >> 1][2 * (q & 1)] * scale; x1 += acc[ai][bj][m][q >> 1][2 * (q & 1) + 1] * scale;
;                         ss += x0 * x0 + x1 * x1;
;                         const unsigned nh = cvt_pk_bf16(x0, x1); wh[q] = nh;
;                         if (MK_LO) wl[2 * bj + (q >> 1)] |= (lo_enc(x0, nh & 0xffffu) | (lo_enc(x1, nh >> 16) << 8)) << (16 * (q & 1)); }
;                     *(u32x4*)(xh + o2) = wh; }
;                 if (MK_LO) *(u32x4*)(xl + lo_addr(u.pm, u.pn, am, wave, lane)) = wl;
;                 ss += __shfl_xor(ss, 16); ss += __shfl_xor(ss, 32);
;                 if (fq == 0) atomicAdd(rowss_out + row, (unsigned)(ss * 1024.0f + 0.5f)); } }
.LBB0_1749:
	s_or_b64 exec, exec, s[48:49]
	v_add_u32_e32 v100, 0x80, v180
	v_ashrrev_i32_e32 v101, 31, v100
	v_lshlrev_b64 v[110:111], 12, v[100:101]
	s_waitcnt lgkmcnt(0)
	v_lshl_add_u64 v[70:71], v[178:179], 0, v[110:111]
	v_mov_b64_e32 v[102:103], v[228:229]
	v_mov_b64_e32 v[104:105], v[230:231]
	v_mov_b64_e32 v[106:107], v[232:233]
	v_mov_b64_e32 v[108:109], v[234:235]
	v_add_u32_e32 v98, 0x90, v180
	v_add_u32_e32 v96, 0xa0, v180
	v_add_u32_e32 v94, 0xb0, v180
	v_ashrrev_i32_e32 v99, 31, v98
	v_ashrrev_i32_e32 v97, 31, v96
	v_ashrrev_i32_e32 v95, 31, v94
	v_lshlrev_b64 v[70:71], 12, v[98:99]
	v_lshlrev_b64 v[72:73], 12, v[96:97]
	v_lshlrev_b64 v[74:75], 12, v[94:95]
	v_lshl_add_u64 v[70:71], v[178:179], 0, v[70:71]
	v_lshl_add_u64 v[72:73], v[178:179], 0, v[72:73]
	v_lshl_add_u64 v[112:113], v[178:179], 0, v[74:75]
	v_mov_b64_e32 v[90:91], v[236:237]
	v_mov_b64_e32 v[92:93], v[238:239]
	v_mov_b64_e32 v[86:87], v[240:241]
	v_mov_b64_e32 v[88:89], v[242:243]
	v_mov_b64_e32 v[82:83], v[244:245]
	v_mov_b64_e32 v[84:85], v[246:247]
	v_mov_b64_e32 v[78:79], v[248:249]
	v_mov_b64_e32 v[80:81], v[250:251]
	v_mov_b64_e32 v[74:75], v[164:165]
	v_mov_b64_e32 v[76:77], v[166:167]
	s_nop 0
	v_mov_b64_e32 v[70:71], v[200:201]
	v_mov_b64_e32 v[72:73], v[202:203]
	v_mov_b64_e32 v[164:165], 0x400
	v_mov_b64_e32 v[166:167], 0x3ff
	v_mov_b32_e32 v200, 0x7f800000
	v_mov_b32_e32 v201, 0x7fc00000
	v_mov_b32_e32 v202, 0xff800000
	v_mov_b32_e32 v203, 0x3000
	v_lshlrev_b32_e32 v112, 16, v102
	v_and_b32_e32 v102, 0xffff0000, v102
	v_lshlrev_b32_e32 v113, 16, v103
	v_and_b32_e32 v103, 0xffff0000, v103
	v_lshlrev_b32_e32 v114, 16, v104
	v_and_b32_e32 v104, 0xffff0000, v104
	v_lshlrev_b32_e32 v115, 16, v105
	v_and_b32_e32 v105, 0xffff0000, v105
	v_add_f32_e32 v59, v59, v102
	v_add_f32_e32 v61, v61, v103
	v_add_f32_e32 v58, v58, v112
	v_add_f32_e32 v60, v60, v113
	v_add_f32_e32 v102, v54, v114
	v_add_f32_e32 v103, v55, v104
	v_add_f32_e32 v57, v57, v105
	v_mul_f32_e32 v105, v59, v59
	v_cvt_pk_bf16_f32 v54, v58, v59
	v_mul_f32_e32 v59, v61, v61
	v_lshlrev_b32_e32 v116, 16, v106
	v_and_b32_e32 v106, 0xffff0000, v106
	v_cvt_pk_bf16_f32 v55, v60, v61
	v_mul_f32_e32 v61, v103, v103
	v_fmac_f32_e32 v105, v58, v58
	v_fmac_f32_e32 v59, v60, v60
	v_lshlrev_b32_e32 v117, 16, v107
	v_and_b32_e32 v107, 0xffff0000, v107
	v_add_f32_e32 v104, v56, v115
	v_add_f32_e32 v67, v67, v106
	v_cvt_pk_bf16_f32 v56, v102, v103
	v_mul_f32_e32 v103, v57, v57
	v_fmac_f32_e32 v61, v102, v102
	v_add_f32_e32 v58, v105, v59
	v_lshlrev_b32_e32 v119, 16, v108
	v_and_b32_e32 v108, 0xffff0000, v108
	v_add_f32_e32 v66, v66, v116
	v_add_f32_e32 v69, v69, v107
	v_mul_f32_e32 v106, v67, v67
	v_fmac_f32_e32 v103, v104, v104
	v_add_f32_e32 v58, v61, v58
	v_lshlrev_b32_e32 v120, 16, v109
	v_and_b32_e32 v109, 0xffff0000, v109
	v_add_f32_e32 v68, v68, v117
	v_add_f32_e32 v63, v63, v108
	v_mul_f32_e32 v107, v69, v69
	v_fmac_f32_e32 v106, v66, v66
	v_add_f32_e32 v58, v103, v58
	v_add_f32_e32 v62, v62, v119
	v_add_f32_e32 v65, v65, v109
	v_mul_f32_e32 v108, v63, v63
	v_fmac_f32_e32 v107, v68, v68
	v_add_f32_e32 v58, v106, v58
	v_add_f32_e32 v64, v64, v120
	v_mul_f32_e32 v109, v65, v65
	v_fmac_f32_e32 v108, v62, v62
	v_add_f32_e32 v58, v107, v58
	v_add_f32_e32 v58, v108, v58
	v_fmac_f32_e32 v109, v64, v64
	v_add_f32_e32 v102, v109, v58
	ds_bpermute_b32 v103, v189, v102
	v_lshl_add_u64 v[58:59], s[96:97], 0, v[110:111]
	v_lshl_add_u64 v[60:61], v[176:177], 1, v[58:59]
	v_cvt_pk_bf16_f32 v57, v104, v57
	global_store_dwordx4 v[60:61], v[54:57], off
	s_waitcnt lgkmcnt(0)
	s_nop 0
	v_add_f32_e32 v54, v102, v103
	ds_bpermute_b32 v55, v118, v54
	v_cvt_pk_bf16_f32 v56, v66, v67
	v_cvt_pk_bf16_f32 v57, v68, v69
	v_cvt_pk_bf16_f32 v58, v62, v63
	v_cvt_pk_bf16_f32 v59, v64, v65
	global_store_dwordx4 v[60:61], v[56:59], off offset:256
	s_and_saveexec_b64 s[48:49], s[36:37]
	s_cbranch_execz .LBB0_1751
	s_waitcnt lgkmcnt(0)
	v_add_f32_e32 v54, v54, v55
	v_fma_f32 v54, v54, s71, 0.5
	v_cvt_u32_f32_e32 v56, v54
	v_lshl_add_u64 v[54:55], v[100:101], 2, s[26:27]
	global_atomic_add v[54:55], v56, off
.LBB0_1751:
	s_or_b64 exec, exec, s[48:49]
	v_and_b32_e32 v57, 0xffff0000, v90
	v_lshlrev_b32_e32 v56, 16, v90
	v_add_f32_e32 v51, v51, v57
	v_add_f32_e32 v50, v50, v56
	v_mul_f32_e32 v56, v51, v51
	v_fmac_f32_e32 v56, v50, v50
	v_cvt_pk_bf16_f32 v50, v50, v51
	v_lshlrev_b32_e32 v51, 16, v91
	v_and_b32_e32 v57, 0xffff0000, v91
	v_add_f32_e32 v51, v52, v51
	v_add_f32_e32 v52, v53, v57
	v_mul_f32_e32 v53, v52, v52
	v_fmac_f32_e32 v53, v51, v51
	v_add_f32_e32 v53, v56, v53
	v_and_b32_e32 v56, 0xffff0000, v92
	v_cvt_pk_bf16_f32 v51, v51, v52
	v_lshlrev_b32_e32 v52, 16, v92
	v_add_f32_e32 v43, v43, v56
	v_add_f32_e32 v42, v42, v52
	v_mul_f32_e32 v52, v43, v43
	v_fmac_f32_e32 v52, v42, v42
	v_add_f32_e32 v53, v52, v53
	v_cvt_pk_bf16_f32 v52, v42, v43
	v_and_b32_e32 v43, 0xffff0000, v93
	v_lshlrev_b32_e32 v42, 16, v93
	v_add_f32_e32 v43, v45, v43
	v_add_f32_e32 v42, v44, v42
	v_mul_f32_e32 v44, v43, v43
	v_fmac_f32_e32 v44, v42, v42
	v_add_f32_e32 v44, v44, v53
	v_cvt_pk_bf16_f32 v53, v42, v43
	v_and_b32_e32 v43, 0xffff0000, v86
	v_lshlrev_b32_e32 v42, 16, v86
	v_add_f32_e32 v43, v47, v43
	v_add_f32_e32 v42, v46, v42
	v_mul_f32_e32 v45, v43, v43
	v_fmac_f32_e32 v45, v42, v42
	v_and_b32_e32 v46, 0xffff0000, v87
	v_add_f32_e32 v44, v45, v44
	v_lshlrev_b32_e32 v45, 16, v87
	v_add_f32_e32 v46, v49, v46
	v_add_f32_e32 v47, v48, v45
	v_mul_f32_e32 v45, v46, v46
	v_fmac_f32_e32 v45, v47, v47
	v_and_b32_e32 v48, 0xffff0000, v88
	v_add_f32_e32 v44, v45, v44
	v_lshlrev_b32_e32 v45, 16, v88
	v_add_f32_e32 v48, v39, v48
	v_add_f32_e32 v49, v38, v45
	v_mul_f32_e32 v38, v48, v48
	v_fmac_f32_e32 v38, v49, v49
	v_add_f32_e32 v38, v38, v44
	v_and_b32_e32 v44, 0xffff0000, v89
	v_lshlrev_b32_e32 v39, 16, v89
	v_add_f32_e32 v57, v41, v44
	v_add_f32_e32 v56, v40, v39
	v_mul_f32_e32 v39, v57, v57
	v_fmac_f32_e32 v39, v56, v56
	v_add_f32_e32 v41, v39, v38
	ds_bpermute_b32 v58, v189, v41
	s_waitcnt lgkmcnt(1)
	v_lshlrev_b64 v[54:55], 11, v[98:99]
	v_lshl_add_u64 v[38:39], v[54:55], 1, s[96:97]
	v_lshl_add_u64 v[44:45], v[176:177], 1, v[38:39]
	global_store_dwordx4 v[44:45], v[50:53], off
	s_waitcnt lgkmcnt(0)
	v_add_f32_e32 v38, v41, v58
	ds_bpermute_b32 v39, v118, v38
	v_cvt_pk_bf16_f32 v40, v42, v43
	v_cvt_pk_bf16_f32 v41, v47, v46
	v_cvt_pk_bf16_f32 v42, v49, v48
	v_cvt_pk_bf16_f32 v43, v56, v57
	global_store_dwordx4 v[44:45], v[40:43], off offset:256
	s_and_saveexec_b64 s[48:49], s[36:37]
	s_cbranch_execz .LBB0_1753
	s_waitcnt lgkmcnt(0)
	v_add_f32_e32 v38, v38, v39
	v_fma_f32 v38, v38, s71, 0.5
	v_cvt_u32_f32_e32 v40, v38
	v_lshl_add_u64 v[38:39], v[98:99], 2, s[26:27]
	global_atomic_add v[38:39], v40, off
; __device__ __forceinline__ unsigned cvt_pk_bf16(float lo, float hi) { unsigned r; asm volatile("v_cvt_pk_bf16_f32 %0, %1, %2" : "=v"(r) : "v"(lo), "v"(hi)); return r; }
; __device__ __forceinline__ float lo_dec(unsigned hb, unsigned byte) { return ((float)byte - 128.0f) * lo_scale(hb); }
; __device__ __forceinline__ unsigned lo_enc(float x, unsigned hb) { const float hf = __builtin_bit_cast(float, hb << 16); float t = (x - hf) * lo_inv(hb) + 128.0f; t = fminf(fmaxf(t, 1.0f), 255.0f); return (unsigned)__builtin_rintf(t); }
; __device__ __forceinline__ size_t lo_addr(int pm, int pn, int am, int wave, int lane) { return ((((size_t)(pm * 8 + pn) * 8 + am) * 8 + wave) * 64 + lane) * 16; }
;     __device__ __forceinline__ void operator()(const f32x4 (&acc)[2][2][4][2], const Unit& u, int wr, int wc, int fr, int fq, const Pre&) const {
;     ...
;             for (int mm = 0; mm < NB; ++mm) { const int am = NB * ab + mm, ai = am >> 2, m = am & 3; const int row = row0 + ai * HALF + m * 16; float ss = 0.f; u32x4 wl = {0u, 0u, 0u, 0u};
; #pragma unroll
;                 for (int bj = 0; bj < 2; ++bj) { const size_t o2 = (size_t)row * ldc + col0 + bj * HALF; u32x4 wh;
; #pragma unroll
;                     for (int q = 0; q < 4; ++q) { const unsigned h = hi[mm][bj][q], lw = lo[mm][2 * bj + (q >> 1)] >> (16 * (q & 1));
;                         float x0 = __builtin_bit_cast(float, h << 16), x1 = __builtin_bit_cast(float, h & 0xffff0000u); if (MK_LO) { x0 += lo_dec(h & 0xffffu, lw & 0xffu); x1 += lo_dec(h >> 16, (lw >> 8) & 0xffu); }
;                         x0 += acc[ai][bj][m][q >> 1][2 * (q & 1)] * scale; x1 += acc[ai][bj][m][q >> 1][2 * (q & 1) + 1] * scale;
;                         ss += x0 * x0 + x1 * x1;
;                         const unsigned nh = cvt_pk_bf16(x0, x1); wh[q] = nh;
;                         if (MK_LO) wl[2 * bj + (q >> 1)] |= (lo_enc(x0, nh & 0xffffu) | (lo_enc(x1, nh >> 16) << 8)) << (16 * (q & 1)); }
;                     *(u32x4*)(xh + o2) = wh; }
;                 if (MK_LO) *(u32x4*)(xl + lo_addr(u.pm, u.pn, am, wave, lane)) = wl;
;                 ss += __shfl_xor(ss, 16); ss += __shfl_xor(ss, 32);
;                 if (fq == 0) atomicAdd(rowss_out + row, (unsigned)(ss * 1024.0f + 0.5f)); } }
.LBB0_1753:
	s_or_b64 exec, exec, s[48:49]
	v_and_b32_e32 v41, 0xffff0000, v82
	v_lshlrev_b32_e32 v40, 16, v82
	v_add_f32_e32 v35, v35, v41
	v_add_f32_e32 v34, v34, v40
	v_mul_f32_e32 v40, v35, v35
	v_fmac_f32_e32 v40, v34, v34
	v_cvt_pk_bf16_f32 v34, v34, v35
	v_lshlrev_b32_e32 v35, 16, v83
	v_and_b32_e32 v41, 0xffff0000, v83
	v_add_f32_e32 v35, v36, v35
	v_add_f32_e32 v36, v37, v41
	v_mul_f32_e32 v37, v36, v36
	v_fmac_f32_e32 v37, v35, v35
	v_add_f32_e32 v37, v40, v37
	v_and_b32_e32 v40, 0xffff0000, v84
	v_cvt_pk_bf16_f32 v35, v35, v36
	v_lshlrev_b32_e32 v36, 16, v84
	v_add_f32_e32 v27, v27, v40
	v_add_f32_e32 v26, v26, v36
	v_mul_f32_e32 v36, v27, v27
	v_fmac_f32_e32 v36, v26, v26
	v_add_f32_e32 v37, v36, v37
	v_cvt_pk_bf16_f32 v36, v26, v27
	v_and_b32_e32 v27, 0xffff0000, v85
	v_lshlrev_b32_e32 v26, 16, v85
	v_add_f32_e32 v27, v29, v27
	v_add_f32_e32 v26, v28, v26
	v_mul_f32_e32 v28, v27, v27
	v_fmac_f32_e32 v28, v26, v26
	v_add_f32_e32 v28, v28, v37
	v_cvt_pk_bf16_f32 v37, v26, v27
	v_and_b32_e32 v27, 0xffff0000, v78
	v_lshlrev_b32_e32 v26, 16, v78
	v_add_f32_e32 v27, v31, v27
	v_add_f32_e32 v26, v30, v26
	v_mul_f32_e32 v29, v27, v27
	v_fmac_f32_e32 v29, v26, v26
	v_and_b32_e32 v30, 0xffff0000, v79
	v_add_f32_e32 v28, v29, v28
	v_lshlrev_b32_e32 v29, 16, v79
	v_add_f32_e32 v30, v33, v30
	v_add_f32_e32 v31, v32, v29
	v_mul_f32_e32 v29, v30, v30
	v_fmac_f32_e32 v29, v31, v31
	v_and_b32_e32 v32, 0xffff0000, v80
	v_add_f32_e32 v28, v29, v28
	v_lshlrev_b32_e32 v29, 16, v80
	v_add_f32_e32 v32, v23, v32
	v_add_f32_e32 v33, v22, v29
	v_mul_f32_e32 v22, v32, v32
	v_fmac_f32_e32 v22, v33, v33
	v_add_f32_e32 v22, v22, v28
	v_and_b32_e32 v28, 0xffff0000, v81
	v_lshlrev_b32_e32 v23, 16, v81
	v_add_f32_e32 v41, v25, v28
	v_add_f32_e32 v40, v24, v23
	v_mul_f32_e32 v23, v41, v41
	v_fmac_f32_e32 v23, v40, v40
	v_add_f32_e32 v25, v23, v22
	ds_bpermute_b32 v42, v189, v25
	s_waitcnt lgkmcnt(1)
	v_lshlrev_b64 v[38:39], 11, v[96:97]
	v_lshl_add_u64 v[22:23], v[38:39], 1, s[96:97]
	v_lshl_add_u64 v[28:29], v[176:177], 1, v[22:23]
	global_store_dwordx4 v[28:29], v[34:37], off
	s_waitcnt lgkmcnt(0)
	v_add_f32_e32 v22, v25, v42
	ds_bpermute_b32 v23, v118, v22
	v_cvt_pk_bf16_f32 v24, v26, v27
	v_cvt_pk_bf16_f32 v25, v31, v30
	v_cvt_pk_bf16_f32 v26, v33, v32
	v_cvt_pk_bf16_f32 v27, v40, v41
	global_store_dwordx4 v[28:29], v[24:27], off offset:256
	s_and_saveexec_b64 s[48:49], s[36:37]
	s_cbranch_execz .LBB0_1755
	s_waitcnt lgkmcnt(0)
	v_add_f32_e32 v22, v22, v23
	v_fma_f32 v22, v22, s71, 0.5
	v_cvt_u32_f32_e32 v24, v22
	v_lshl_add_u64 v[22:23], v[96:97], 2, s[26:27]
	global_atomic_add v[22:23], v24, off
.LBB0_1755:
	s_or_b64 exec, exec, s[48:49]
	v_and_b32_e32 v25, 0xffff0000, v74
	v_lshlrev_b32_e32 v24, 16, v74
	v_add_f32_e32 v19, v19, v25
	v_add_f32_e32 v18, v18, v24
	v_mul_f32_e32 v24, v19, v19
	v_fmac_f32_e32 v24, v18, v18
	v_cvt_pk_bf16_f32 v18, v18, v19
	v_lshlrev_b32_e32 v19, 16, v75
	v_and_b32_e32 v25, 0xffff0000, v75
	v_add_f32_e32 v19, v20, v19
	v_add_f32_e32 v20, v21, v25
	v_mul_f32_e32 v21, v20, v20
	v_fmac_f32_e32 v21, v19, v19
	v_add_f32_e32 v21, v24, v21
	v_and_b32_e32 v24, 0xffff0000, v76
	v_cvt_pk_bf16_f32 v19, v19, v20
	v_lshlrev_b32_e32 v20, 16, v76
	v_add_f32_e32 v11, v11, v24
	v_add_f32_e32 v10, v10, v20
	v_mul_f32_e32 v20, v11, v11
	v_fmac_f32_e32 v20, v10, v10
	v_add_f32_e32 v21, v20, v21
	v_cvt_pk_bf16_f32 v20, v10, v11
	v_and_b32_e32 v11, 0xffff0000, v77
	v_lshlrev_b32_e32 v10, 16, v77
	v_add_f32_e32 v11, v13, v11
	v_add_f32_e32 v10, v12, v10
	v_mul_f32_e32 v12, v11, v11
	v_fmac_f32_e32 v12, v10, v10
	v_add_f32_e32 v12, v12, v21
	v_cvt_pk_bf16_f32 v21, v10, v11
	v_and_b32_e32 v11, 0xffff0000, v70
	v_lshlrev_b32_e32 v10, 16, v70
	v_add_f32_e32 v11, v15, v11
	v_add_f32_e32 v10, v14, v10
	v_mul_f32_e32 v13, v11, v11
	v_fmac_f32_e32 v13, v10, v10
	v_and_b32_e32 v14, 0xffff0000, v71
	v_add_f32_e32 v12, v13, v12
	v_lshlrev_b32_e32 v13, 16, v71
	v_add_f32_e32 v14, v17, v14
	v_add_f32_e32 v15, v16, v13
	v_mul_f32_e32 v13, v14, v14
	v_fmac_f32_e32 v13, v15, v15
	v_and_b32_e32 v16, 0xffff0000, v72
	v_add_f32_e32 v12, v13, v12
	v_lshlrev_b32_e32 v13, 16, v72
	v_add_f32_e32 v16, v7, v16
	v_add_f32_e32 v17, v6, v13
	v_mul_f32_e32 v6, v16, v16
	v_fmac_f32_e32 v6, v17, v17
	v_add_f32_e32 v6, v6, v12
	v_and_b32_e32 v12, 0xffff0000, v73
	v_lshlrev_b32_e32 v7, 16, v73
	v_add_f32_e32 v25, v9, v12
	v_add_f32_e32 v24, v8, v7
	v_mul_f32_e32 v7, v25, v25
	v_fmac_f32_e32 v7, v24, v24
	v_add_f32_e32 v9, v7, v6
	ds_bpermute_b32 v26, v189, v9
	s_waitcnt lgkmcnt(1)
	v_lshlrev_b64 v[22:23], 11, v[94:95]
	v_lshl_add_u64 v[6:7], v[22:23], 1, s[96:97]
	v_lshl_add_u64 v[12:13], v[176:177], 1, v[6:7]
	global_store_dwordx4 v[12:13], v[18:21], off
	s_waitcnt lgkmcnt(0)
	v_add_f32_e32 v6, v9, v26
	ds_bpermute_b32 v7, v118, v6
	v_cvt_pk_bf16_f32 v8, v10, v11
	v_cvt_pk_bf16_f32 v9, v15, v14
	v_cvt_pk_bf16_f32 v10, v17, v16
	v_cvt_pk_bf16_f32 v11, v24, v25
	global_store_dwordx4 v[12:13], v[8:11], off offset:256
	s_and_saveexec_b64 s[48:49], s[36:37]
	s_cbranch_execz .LBB0_1757
	s_waitcnt lgkmcnt(0)
	v_add_f32_e32 v6, v6, v7
	v_fma_f32 v6, v6, s71, 0.5
	v_cvt_u32_f32_e32 v6, v6
	v_lshl_add_u64 v[8:9], v[94:95], 2, s[26:27]
	global_atomic_add v[8:9], v6, off
